# in-proj GEMM epilogue: rstd loads hoisted into the tile prologue (issued with the stage loads) instead of an exposed load+wait after the k-loop
# speedup vs baseline: 1.0047x; 1.0047x over previous
; template <bool IN_PROJ>
; DI void gemm_tile(const Params& p, int layer, int nt, int tt, char* smem) {
;     ...
;   const __amdgpu_buffer_rsrc_t rA = __builtin_amdgcn_make_buffer_rsrc((void*)(Wt + (size_t)n0 * DM), 0, 0x7fffffff, 0x00020000);
;   const __amdgpu_buffer_rsrc_t rB0 = __builtin_amdgcn_make_buffer_rsrc((void*)(IN_PROJ ? xb + (size_t)t0 * DM : mixA + (size_t)t0 * 512), 0, 0x7fffffff, 0x00020000);
;   const __amdgpu_buffer_rsrc_t rB1 = __builtin_amdgcn_make_buffer_rsrc((void*)(mixB + (size_t)t0 * 256), 0, 0x7fffffff, 0x00020000);
;   const __amdgpu_buffer_rsrc_t rB2 = __builtin_amdgcn_make_buffer_rsrc((void*)(mixC + (size_t)t0 * 256), 0, 0x7fffffff, 0x00020000);
;   int voA[4], rowB[2], lcB[2];
; #pragma unroll
;   for (int i = 0; i < 4; ++i) { int c = tid + 256 * i; int row = c >> 2, lc = (c & 3) ^ ((row >> 2) & 3); voA[i] = row * (DM * 2) + lc * 16; }
; #pragma unroll
;   for (int i = 0; i < 2; ++i) { int c = tid + 256 * i; rowB[i] = c >> 2; lcB[i] = ((c & 3) ^ ((rowB[i] >> 2) & 3)) * 16; }
;   auto stage = [&](int kt) {
;     const int k0 = kt * 32;
;     char* base = smem + (kt % 3) * G_STAGE + w * 1024;
; #pragma unroll
;     for (int i = 0; i < 4; ++i)
;       __builtin_amdgcn_raw_ptr_buffer_load_lds(rA, (lds_ptr_t)(base + i * 4096), 16, voA[i], k0 * 2, 0, 0);
; #pragma unroll
;     for (int i = 0; i < 2; ++i) {
;       lds_ptr_t dst = (lds_ptr_t)(base + 16384 + i * 4096);
;       if (IN_PROJ) __builtin_amdgcn_raw_ptr_buffer_load_lds(rB0, dst, 16, rowB[i] * (DM * 2) + lcB[i], k0 * 2, 0, 0);
;       else {
;         if (k0 < 512) __builtin_amdgcn_raw_ptr_buffer_load_lds(rB0, dst, 16, rowB[i] * 1024 + lcB[i], k0 * 2, 0, 0);
;         else if (k0 < 768) __builtin_amdgcn_raw_ptr_buffer_load_lds(rB1, dst, 16, rowB[i] * 512 + lcB[i], (k0 - 512) * 2, 0, 0);
;         else __builtin_amdgcn_raw_ptr_buffer_load_lds(rB2, dst, 16, rowB[i] * 512 + lcB[i], (k0 - 768) * 2, 0, 0);
;       }
;     }
;   };
;   asm volatile("s_waitcnt vmcnt(0)" ::: "memory");
;   __syncthreads();
;   stage(0); stage(1); stage(2);
; template <bool IN_PROJ>
; DI void gemm_phase(const Params& p, int layer, char* smem) {
;     ...
;       __syncthreads();
;       if (tidx(p) == 0) *s_tile = (int)atomicAdd(ctr + xq, 1u);
;       __syncthreads();
;       const int q = __builtin_amdgcn_readfirstlane(*s_tile);
;       if (q >= PER_XCD) break;
;       int grp = q / (8 * NT), rem = q % (8 * NT);
.LBB0_70:
	s_or_b64 exec, exec, s[0:1]
	s_waitcnt lgkmcnt(0)
	s_barrier
	ds_read_b32 v0, v242
	s_mov_b64 s[0:1], -1
	s_waitcnt lgkmcnt(0)
	v_readfirstlane_b32 s2, v0
	s_cmpk_gt_i32 s2, 0x32f
	s_cbranch_scc1 .LBB0_65
	s_mul_hi_i32 s0, s2, 0x78787879
	s_lshr_b32 s1, s0, 31
	s_ashr_i32 s0, s0, 6
	s_add_i32 s1, s0, s1
	s_mul_i32 s0, s1, 0x88
	s_sub_i32 s2, s2, s0
	s_ashr_i32 s82, s2, 3
	s_lshl_b32 s2, s2, 3
	s_lshl_b32 s1, s1, 6
	s_and_b32 s2, s2, 56
	v_mov_b32_e32 v0, v234
	s_or_b32 s1, s2, s1
	s_lshl_b32 s94, s82, 8
	v_add_u32_e32 v247, s33, v0
	s_or_b32 s72, s1, s81
	s_ashr_i32 s95, s94, 31
	v_readfirstlane_b32 s60, v247
	s_ashr_i32 s1, s60, 6
	s_ashr_i32 s75, s60, 7
	s_lshl_b32 s92, s72, 7
	s_lshl_b64 s[2:3], s[94:95], 11
	s_add_u32 s4, s67, s2
	s_addc_u32 s5, s80, s3
	s_ashr_i32 s93, s92, 31
	s_lshl_b64 s[2:3], s[92:93], 11
	s_add_u32 s8, s48, s2
	v_lshlrev_b32_e32 v2, 4, v247
	s_addc_u32 s2, s49, s3
	v_lshlrev_b32_e32 v1, 9, v247
	v_bitop3_b32 v2, v2, 48, v247 bitop3:0x48
	s_and_b32 s3, s1, 1
	s_lshl_b32 s1, s1, 10
	v_and_or_b32 v181, v1, s86, v2
	s_and_b32 s5, s5, 0xffff
	s_mov_b32 m0, s1
	v_add_u32_e32 v182, 0x20000, v181
	s_waitcnt vmcnt(0)
	s_barrier
	buffer_load_dwordx4 v181, s[4:7], 0 offen lds
	s_add_i32 m0, s1, 0x1000
	v_add_u32_e32 v183, 0x40000, v181
	buffer_load_dwordx4 v182, s[4:7], 0 offen lds
	s_add_i32 m0, s1, 0x2000
	v_add_u32_e32 v184, 0x60000, v181
	v_add_u32_e32 v248, 0x100, v247
	buffer_load_dwordx4 v183, s[4:7], 0 offen lds
	s_add_i32 m0, s1, 0x3000
	s_and_b32 s9, s2, 0xffff
	s_mov_b32 s10, s6
	s_mov_b32 s11, s7
	buffer_load_dwordx4 v184, s[4:7], 0 offen lds
	s_add_i32 m0, s1, 0x4000
	v_lshlrev_b32_e32 v1, 9, v248
	buffer_load_dwordx4 v181, s[8:11], 0 offen lds
	s_add_i32 m0, s1, 0x5000
	v_and_or_b32 v185, v1, s86, v2
	buffer_load_dwordx4 v185, s[8:11], 0 offen lds
	s_add_i32 m0, s1, 0x6000
	v_lshrrev_b32_e32 v0, 5, v247
	buffer_load_dwordx4 v181, s[4:7], 64 offen lds
	s_add_i32 m0, s1, 0x7000
	v_and_b32_e32 v199, 31, v247
	buffer_load_dwordx4 v182, s[4:7], 64 offen lds
	s_add_i32 m0, s1, 0x8000
	v_bfe_u32 v3, v247, 2, 2
	buffer_load_dwordx4 v183, s[4:7], 64 offen lds
	s_add_i32 m0, s1, 0x9000
	v_lshlrev_b32_e32 v1, 5, v199
	buffer_load_dwordx4 v184, s[4:7], 64 offen lds
	s_add_i32 m0, s1, 0xa000
	v_bitop3_b32 v0, v0, v3, 1 bitop3:0x6c
	buffer_load_dwordx4 v181, s[8:11], 64 offen lds
	s_add_i32 m0, s1, 0xb000
	s_and_b32 s2, s60, 0x7ffff80
	buffer_load_dwordx4 v185, s[8:11], 64 offen lds
	s_add_i32 m0, s1, 0xc000
	v_lshl_or_b32 v2, s75, 12, v1
	buffer_load_dwordx4 v181, s[4:7], s87 offen lds
	s_add_i32 m0, s1, 0xd000
	v_lshlrev_b32_e32 v0, 3, v0
	buffer_load_dwordx4 v182, s[4:7], s87 offen lds
	s_add_i32 m0, s1, 0xe000
	v_or_b32_e32 v4, s2, v199
	buffer_load_dwordx4 v183, s[4:7], s87 offen lds
	s_add_i32 m0, s1, 0xf000
	v_or_b32_e32 v189, v0, v2
	buffer_load_dwordx4 v184, s[4:7], s87 offen lds
	s_add_i32 m0, s1, 0x10000
	v_lshlrev_b32_e32 v4, 5, v4
	buffer_load_dwordx4 v181, s[8:11], s87 offen lds
	s_add_i32 m0, s1, 0x11000
	s_lshl_b32 s74, s3, 6
	buffer_load_dwordx4 v185, s[8:11], s87 offen lds
	v_lshlrev_b32_e32 v177, 1, v189
	v_or_b32_e32 v190, v4, v0
	v_lshl_or_b32 v1, s3, 11, v1
	v_or_b32_e32 v192, s74, v199
	v_readlane_b32 s98, v249, 10
	v_readlane_b32 s99, v249, 11
	v_or_b32_e32 v206, s92, v192
	v_ashrrev_i32_e32 v207, 31, v206
	v_lshl_add_u64 v[206:207], v[206:207], 2, s[98:99]
	global_load_dword v204, v[206:207], off
	global_load_dword v205, v[206:207], off offset:128
	s_waitcnt vmcnt(12)
	s_waitcnt vmcnt(0)
	s_barrier
; #define MFMA32(a, b, c) __builtin_amdgcn_mfma_f32_32x32x16_bf16((a), (b), (c), 0, 0, 0)
; template <bool IN_PROJ>
; DI void gemm_tile(const Params& p, int layer, int nt, int tt, char* smem) {
;     ...
;   f32x16 acc[4][2];
; #pragma unroll
;   for (int a = 0; a < 4; ++a)
; #pragma unroll
;     for (int b = 0; b < 2; ++b)
; #pragma unroll
;       for (int i = 0; i < 16; ++i) acc[a][b][i] = 0.f;
;     ...
;   auto load_frags = [&](int kt, int ks, bf16x8 (&fa)[4], bf16x8 (&fb)[2]) {
;     const u16* sA = (const u16*)(smem + (kt % 3) * G_STAGE);
;     const u16* sB = sA + 8192;
; #pragma unroll
;     for (int fi = 0; fi < 4; ++fi) fa[fi] = *(const bf16x8*)(sA + gswz(wf * 128 + fi * 32 + r, ks * 2 + h));
; #pragma unroll
;     for (int ti = 0; ti < 2; ++ti) fb[ti] = *(const bf16x8*)(sB + gswz(wt * 64 + ti * 32 + r, ks * 2 + h));
;   };
;   auto mma = [&](const bf16x8 (&fa)[4], const bf16x8 (&fb)[2]) {
; #pragma unroll
;     for (int fi = 0; fi < 4; ++fi)
; #pragma unroll
;       for (int ti = 0; ti < 2; ++ti) acc[fi][ti] = MFMA32(fa[fi], fb[ti], acc[fi][ti]);
;   };
;   bf16x8 fa0[4], fb0[2], fa1[4], fb1[2];
;   asm volatile("s_waitcnt vmcnt(12)" ::: "memory");
;   __syncthreads();
;   load_frags(0, 0, fa0, fb0);
	v_lshlrev_b32_e32 v176, 1, v190
	ds_read_b128 v[132:135], v177
	ds_read_b128 v[104:107], v176 offset:2048
	ds_read_b128 v[100:103], v176 offset:4096
	ds_read_b128 v[96:99], v176 offset:6144
	v_or_b32_e32 v191, v1, v0
	v_lshlrev_b32_e32 v5, 5, v192
	v_lshlrev_b32_e32 v178, 1, v191
	v_or_b32_e32 v194, v5, v0
	v_lshlrev_b32_e32 v179, 1, v194
	ds_read_b128 v[128:131], v178 offset:16384
	ds_read_b128 v[108:111], v179 offset:18432
	v_bfe_u32 v198, v247, 5, 1
	v_bitop3_b32 v0, v198, v3, 2 bitop3:0x36
	v_lshlrev_b32_e32 v0, 3, v0
	v_mov_b32_e32 v64, 0
	s_mov_b32 s0, 3
	v_or_b32_e32 v188, v0, v2
	v_or_b32_e32 v187, v0, v1
	v_or_b32_e32 v186, v0, v4
	v_or_b32_e32 v180, v5, v0
	s_movk_i32 s2, 0xc0
	v_mov_b32_e32 v65, v64
	v_mov_b32_e32 v66, v64
	v_mov_b32_e32 v67, v64
	v_mov_b32_e32 v68, v64
	v_mov_b32_e32 v69, v64
	v_mov_b32_e32 v70, v64
	v_mov_b32_e32 v71, v64
	v_mov_b32_e32 v72, v64
	v_mov_b32_e32 v73, v64
	v_mov_b32_e32 v74, v64
	v_mov_b32_e32 v75, v64
	v_mov_b32_e32 v76, v64
	v_mov_b32_e32 v77, v64
	v_mov_b32_e32 v78, v64
	v_mov_b32_e32 v79, v64
	v_mov_b32_e32 v0, v64
	v_mov_b32_e32 v1, v64
	v_mov_b32_e32 v2, v64
	v_mov_b32_e32 v3, v64
	v_mov_b32_e32 v4, v64
	v_mov_b32_e32 v5, v64
	v_mov_b32_e32 v6, v64
	v_mov_b32_e32 v7, v64
	v_mov_b32_e32 v8, v64
	v_mov_b32_e32 v9, v64
	v_mov_b32_e32 v10, v64
	v_mov_b32_e32 v11, v64
	v_mov_b32_e32 v12, v64
	v_mov_b32_e32 v13, v64
	v_mov_b32_e32 v14, v64
	v_mov_b32_e32 v15, v64
	v_mov_b32_e32 v80, v64
	v_mov_b32_e32 v81, v64
	v_mov_b32_e32 v82, v64
	v_mov_b32_e32 v83, v64
	v_mov_b32_e32 v84, v64
	v_mov_b32_e32 v85, v64
	v_mov_b32_e32 v86, v64
	v_mov_b32_e32 v87, v64
	v_mov_b32_e32 v88, v64
	v_mov_b32_e32 v89, v64
	v_mov_b32_e32 v90, v64
	v_mov_b32_e32 v91, v64
	v_mov_b32_e32 v92, v64
	v_mov_b32_e32 v93, v64
	v_mov_b32_e32 v94, v64
	v_mov_b32_e32 v95, v64
	v_mov_b32_e32 v16, v64
	v_mov_b32_e32 v17, v64
	v_mov_b32_e32 v18, v64
	v_mov_b32_e32 v19, v64
	v_mov_b32_e32 v20, v64
	v_mov_b32_e32 v21, v64
	v_mov_b32_e32 v22, v64
	v_mov_b32_e32 v23, v64
	v_mov_b32_e32 v24, v64
	v_mov_b32_e32 v25, v64
	v_mov_b32_e32 v26, v64
	v_mov_b32_e32 v27, v64
	v_mov_b32_e32 v28, v64
	v_mov_b32_e32 v29, v64
	v_mov_b32_e32 v30, v64
	v_mov_b32_e32 v31, v64
	v_mov_b32_e32 v112, v64
	v_mov_b32_e32 v113, v64
	v_mov_b32_e32 v114, v64
	v_mov_b32_e32 v115, v64
	v_mov_b32_e32 v116, v64
	v_mov_b32_e32 v117, v64
	v_mov_b32_e32 v118, v64
	v_mov_b32_e32 v119, v64
	v_mov_b32_e32 v120, v64
	v_mov_b32_e32 v121, v64
	v_mov_b32_e32 v122, v64
	v_mov_b32_e32 v123, v64
	v_mov_b32_e32 v124, v64
	v_mov_b32_e32 v125, v64
	v_mov_b32_e32 v126, v64
	v_mov_b32_e32 v127, v64
	v_mov_b32_e32 v32, v64
	v_mov_b32_e32 v33, v64
	v_mov_b32_e32 v34, v64
	v_mov_b32_e32 v35, v64
	v_mov_b32_e32 v36, v64
	v_mov_b32_e32 v37, v64
	v_mov_b32_e32 v38, v64
	v_mov_b32_e32 v39, v64
	v_mov_b32_e32 v40, v64
	v_mov_b32_e32 v41, v64
	v_mov_b32_e32 v42, v64
	v_mov_b32_e32 v43, v64
	v_mov_b32_e32 v44, v64
	v_mov_b32_e32 v45, v64
	v_mov_b32_e32 v46, v64
	v_mov_b32_e32 v47, v64
	v_mov_b32_e32 v144, v64
	v_mov_b32_e32 v145, v64
	v_mov_b32_e32 v146, v64
	v_mov_b32_e32 v147, v64
	v_mov_b32_e32 v148, v64
	v_mov_b32_e32 v149, v64
	v_mov_b32_e32 v150, v64
	v_mov_b32_e32 v151, v64
	v_mov_b32_e32 v152, v64
	v_mov_b32_e32 v153, v64
	v_mov_b32_e32 v154, v64
	v_mov_b32_e32 v155, v64
	v_mov_b32_e32 v156, v64
	v_mov_b32_e32 v157, v64
	v_mov_b32_e32 v158, v64
	v_mov_b32_e32 v159, v64
	v_mov_b32_e32 v48, v64
	v_mov_b32_e32 v49, v64
	v_mov_b32_e32 v50, v64
	v_mov_b32_e32 v51, v64
	v_mov_b32_e32 v52, v64
	v_mov_b32_e32 v53, v64
	v_mov_b32_e32 v54, v64
	v_mov_b32_e32 v55, v64
	v_mov_b32_e32 v56, v64
	v_mov_b32_e32 v57, v64
	v_mov_b32_e32 v58, v64
	v_mov_b32_e32 v59, v64
	v_mov_b32_e32 v60, v64
	v_mov_b32_e32 v61, v64
	v_mov_b32_e32 v62, v64
	v_mov_b32_e32 v63, v64

; template <bool IN_PROJ>
; DI void gemm_tile(const Params& p, int layer, int nt, int tt, char* smem) {
;     ...
;   for (int ti = 0; ti < 2; ++ti) {
;     const int t = t0 + wt * 64 + ti * 32 + r;
;     const float rs = rstd[t];
; #pragma unroll
;     for (int fi = 0; fi < 4; ++fi)
; #pragma unroll
;       for (int i = 0; i < 16; ++i) acc[fi][ti][i] *= rs;
;     if (d.kind == K_SILU) {
.LBB0_89:
	s_xor_b64 s[4:5], s[0:1], -1
	v_or_b32_e32 v96, s92, v192
	v_readlane_b32 s0, v249, 10
	v_ashrrev_i32_e32 v97, 31, v96
	v_readlane_b32 s1, v249, 11
	s_xor_b64 s[8:9], s[2:3], -1
	s_mov_b64 s[64:65], -1
	v_lshl_add_u64 v[194:195], v[96:97], 2, s[0:1]
	v_mov_b32_e32 v160, v204
	s_mov_b64 s[10:11], 0
	s_cmp_lt_i32 s73, 2
	s_mov_b64 s[2:3], 0
	s_mov_b64 s[0:1], 0
	s_mov_b64 s[60:61], 0
	s_waitcnt vmcnt(0)
	v_pk_mul_f32 v[128:129], v[64:65], v[160:161] op_sel_hi:[1,0]
	v_pk_mul_f32 v[130:131], v[66:67], v[160:161] op_sel_hi:[1,0]
	v_pk_mul_f32 v[132:133], v[68:69], v[160:161] op_sel_hi:[1,0]
	v_pk_mul_f32 v[134:135], v[70:71], v[160:161] op_sel_hi:[1,0]
	v_pk_mul_f32 v[136:137], v[72:73], v[160:161] op_sel_hi:[1,0]
	v_pk_mul_f32 v[138:139], v[74:75], v[160:161] op_sel_hi:[1,0]
	v_pk_mul_f32 v[140:141], v[76:77], v[160:161] op_sel_hi:[1,0]
	v_pk_mul_f32 v[142:143], v[78:79], v[160:161] op_sel_hi:[1,0]
	v_pk_mul_f32 v[96:97], v[80:81], v[160:161] op_sel_hi:[1,0]
	v_pk_mul_f32 v[98:99], v[82:83], v[160:161] op_sel_hi:[1,0]
	v_pk_mul_f32 v[100:101], v[84:85], v[160:161] op_sel_hi:[1,0]
	v_pk_mul_f32 v[102:103], v[86:87], v[160:161] op_sel_hi:[1,0]
	v_pk_mul_f32 v[104:105], v[88:89], v[160:161] op_sel_hi:[1,0]
	v_pk_mul_f32 v[106:107], v[90:91], v[160:161] op_sel_hi:[1,0]
	v_pk_mul_f32 v[108:109], v[92:93], v[160:161] op_sel_hi:[1,0]
	v_pk_mul_f32 v[110:111], v[94:95], v[160:161] op_sel_hi:[1,0]
	v_pk_mul_f32 v[80:81], v[112:113], v[160:161] op_sel_hi:[1,0]
	v_pk_mul_f32 v[82:83], v[114:115], v[160:161] op_sel_hi:[1,0]
	v_pk_mul_f32 v[84:85], v[116:117], v[160:161] op_sel_hi:[1,0]
	v_pk_mul_f32 v[86:87], v[118:119], v[160:161] op_sel_hi:[1,0]
	v_pk_mul_f32 v[88:89], v[120:121], v[160:161] op_sel_hi:[1,0]
	v_pk_mul_f32 v[90:91], v[122:123], v[160:161] op_sel_hi:[1,0]
	v_pk_mul_f32 v[92:93], v[124:125], v[160:161] op_sel_hi:[1,0]
	v_pk_mul_f32 v[94:95], v[126:127], v[160:161] op_sel_hi:[1,0]
	v_pk_mul_f32 v[64:65], v[144:145], v[160:161] op_sel_hi:[1,0]
	v_pk_mul_f32 v[66:67], v[146:147], v[160:161] op_sel_hi:[1,0]
	v_pk_mul_f32 v[68:69], v[148:149], v[160:161] op_sel_hi:[1,0]
	v_pk_mul_f32 v[70:71], v[150:151], v[160:161] op_sel_hi:[1,0]
	v_pk_mul_f32 v[72:73], v[152:153], v[160:161] op_sel_hi:[1,0]
	v_pk_mul_f32 v[74:75], v[154:155], v[160:161] op_sel_hi:[1,0]
	v_pk_mul_f32 v[76:77], v[156:157], v[160:161] op_sel_hi:[1,0]
	v_pk_mul_f32 v[78:79], v[158:159], v[160:161] op_sel_hi:[1,0]
	s_cbranch_scc1 .LBB0_101
	s_cmp_gt_i32 s73, 4
	s_cbranch_scc0 .LBB0_93
	s_mov_b64 s[60:61], -1
	s_mov_b64 s[64:65], 0
	s_cmp_eq_u32 s73, 5
	s_cbranch_scc0 .LBB0_93
	s_mov_b64 s[60:61], 0
	s_mov_b64 s[2:3], -1

; template <bool IN_PROJ>
; DI void gemm_tile(const Params& p, int layer, int nt, int tt, char* smem) {
;     ...
;   for (int ti = 0; ti < 2; ++ti) {
;     const int t = t0 + wt * 64 + ti * 32 + r;
;     const float rs = rstd[t];
; #pragma unroll
;     for (int fi = 0; fi < 4; ++fi)
; #pragma unroll
;       for (int i = 0; i < 16; ++i) acc[fi][ti][i] *= rs;
;     if (d.kind == K_SILU) {
.LBB0_173:
	v_mov_b32_e32 v96, v205
	s_mov_b64 s[64:65], -1
	s_mov_b64 s[10:11], 0
	s_cmp_lt_i32 s73, 2
	s_mov_b64 s[2:3], 0
	s_mov_b64 s[0:1], 0
	s_mov_b64 s[60:61], 0
	s_waitcnt vmcnt(0)
	v_pk_mul_f32 v[80:81], v[0:1], v[96:97] op_sel_hi:[1,0]
	v_pk_mul_f32 v[82:83], v[2:3], v[96:97] op_sel_hi:[1,0]
	v_pk_mul_f32 v[84:85], v[4:5], v[96:97] op_sel_hi:[1,0]
	v_pk_mul_f32 v[86:87], v[6:7], v[96:97] op_sel_hi:[1,0]
	v_pk_mul_f32 v[88:89], v[8:9], v[96:97] op_sel_hi:[1,0]
	v_pk_mul_f32 v[90:91], v[10:11], v[96:97] op_sel_hi:[1,0]
	v_pk_mul_f32 v[92:93], v[12:13], v[96:97] op_sel_hi:[1,0]
	v_pk_mul_f32 v[94:95], v[14:15], v[96:97] op_sel_hi:[1,0]
	v_pk_mul_f32 v[64:65], v[16:17], v[96:97] op_sel_hi:[1,0]
	v_pk_mul_f32 v[66:67], v[18:19], v[96:97] op_sel_hi:[1,0]
	v_pk_mul_f32 v[68:69], v[20:21], v[96:97] op_sel_hi:[1,0]
	v_pk_mul_f32 v[70:71], v[22:23], v[96:97] op_sel_hi:[1,0]
	v_pk_mul_f32 v[72:73], v[24:25], v[96:97] op_sel_hi:[1,0]
	v_pk_mul_f32 v[74:75], v[26:27], v[96:97] op_sel_hi:[1,0]
	v_pk_mul_f32 v[76:77], v[28:29], v[96:97] op_sel_hi:[1,0]
	v_pk_mul_f32 v[78:79], v[30:31], v[96:97] op_sel_hi:[1,0]
	v_pk_mul_f32 v[16:17], v[32:33], v[96:97] op_sel_hi:[1,0]
	v_pk_mul_f32 v[18:19], v[34:35], v[96:97] op_sel_hi:[1,0]
	v_pk_mul_f32 v[20:21], v[36:37], v[96:97] op_sel_hi:[1,0]
	v_pk_mul_f32 v[22:23], v[38:39], v[96:97] op_sel_hi:[1,0]
	v_pk_mul_f32 v[24:25], v[40:41], v[96:97] op_sel_hi:[1,0]
	v_pk_mul_f32 v[26:27], v[42:43], v[96:97] op_sel_hi:[1,0]
	v_pk_mul_f32 v[28:29], v[44:45], v[96:97] op_sel_hi:[1,0]
	v_pk_mul_f32 v[30:31], v[46:47], v[96:97] op_sel_hi:[1,0]
	v_pk_mul_f32 v[0:1], v[48:49], v[96:97] op_sel_hi:[1,0]
	v_pk_mul_f32 v[2:3], v[50:51], v[96:97] op_sel_hi:[1,0]
	v_pk_mul_f32 v[4:5], v[52:53], v[96:97] op_sel_hi:[1,0]
	v_pk_mul_f32 v[6:7], v[54:55], v[96:97] op_sel_hi:[1,0]
	v_pk_mul_f32 v[8:9], v[56:57], v[96:97] op_sel_hi:[1,0]
	v_pk_mul_f32 v[10:11], v[58:59], v[96:97] op_sel_hi:[1,0]
	v_pk_mul_f32 v[12:13], v[60:61], v[96:97] op_sel_hi:[1,0]
	v_pk_mul_f32 v[14:15], v[62:63], v[96:97] op_sel_hi:[1,0]
	s_cbranch_scc1 .LBB0_189
	s_cmp_gt_i32 s73, 4
	s_cbranch_scc0 .LBB0_177
	s_mov_b64 s[60:61], -1
	s_mov_b64 s[64:65], 0
	s_cmp_eq_u32 s73, 5
	s_cbranch_scc0 .LBB0_177
	s_mov_b64 s[60:61], 0
	s_mov_b64 s[2:3], -1

; template <bool IN_PROJ>
; DI void gemm_tile(const Params& p, int layer, int nt, int tt, char* smem) {
;     ...
;   const __amdgpu_buffer_rsrc_t rA = __builtin_amdgcn_make_buffer_rsrc((void*)(Wt + (size_t)n0 * DM), 0, 0x7fffffff, 0x00020000);
;   const __amdgpu_buffer_rsrc_t rB0 = __builtin_amdgcn_make_buffer_rsrc((void*)(IN_PROJ ? xb + (size_t)t0 * DM : mixA + (size_t)t0 * 512), 0, 0x7fffffff, 0x00020000);
;   const __amdgpu_buffer_rsrc_t rB1 = __builtin_amdgcn_make_buffer_rsrc((void*)(mixB + (size_t)t0 * 256), 0, 0x7fffffff, 0x00020000);
;   const __amdgpu_buffer_rsrc_t rB2 = __builtin_amdgcn_make_buffer_rsrc((void*)(mixC + (size_t)t0 * 256), 0, 0x7fffffff, 0x00020000);
;   int voA[4], rowB[2], lcB[2];
; #pragma unroll
;   for (int i = 0; i < 4; ++i) { int c = tid + 256 * i; int row = c >> 2, lc = (c & 3) ^ ((row >> 2) & 3); voA[i] = row * (DM * 2) + lc * 16; }
; #pragma unroll
;   for (int i = 0; i < 2; ++i) { int c = tid + 256 * i; rowB[i] = c >> 2; lcB[i] = ((c & 3) ^ ((rowB[i] >> 2) & 3)) * 16; }
;   auto stage = [&](int kt) {
;     const int k0 = kt * 32;
;     char* base = smem + (kt % 3) * G_STAGE + w * 1024;
; #pragma unroll
;     for (int i = 0; i < 4; ++i)
;       __builtin_amdgcn_raw_ptr_buffer_load_lds(rA, (lds_ptr_t)(base + i * 4096), 16, voA[i], k0 * 2, 0, 0);
; #pragma unroll
;     for (int i = 0; i < 2; ++i) {
;       lds_ptr_t dst = (lds_ptr_t)(base + 16384 + i * 4096);
;       if (IN_PROJ) __builtin_amdgcn_raw_ptr_buffer_load_lds(rB0, dst, 16, rowB[i] * (DM * 2) + lcB[i], k0 * 2, 0, 0);
;       else {
;         if (k0 < 512) __builtin_amdgcn_raw_ptr_buffer_load_lds(rB0, dst, 16, rowB[i] * 1024 + lcB[i], k0 * 2, 0, 0);
;         else if (k0 < 768) __builtin_amdgcn_raw_ptr_buffer_load_lds(rB1, dst, 16, rowB[i] * 512 + lcB[i], (k0 - 512) * 2, 0, 0);
;         else __builtin_amdgcn_raw_ptr_buffer_load_lds(rB2, dst, 16, rowB[i] * 512 + lcB[i], (k0 - 768) * 2, 0, 0);
;       }
;     }
;   };
;   asm volatile("s_waitcnt vmcnt(0)" ::: "memory");
;   __syncthreads();
;   stage(0); stage(1); stage(2);
; template <bool IN_PROJ>
; DI void gemm_phase(const Params& p, int layer, char* smem) {
;     ...
;       __syncthreads();
;       if (tidx(p) == 0) *s_tile = (int)atomicAdd(ctr + xq, 1u);
;       __syncthreads();
;       const int q = __builtin_amdgcn_readfirstlane(*s_tile);
;       if (q >= PER_XCD) break;
;       int grp = q / (8 * NT), rem = q % (8 * NT);
.LBB0_789:
	s_or_b64 exec, exec, s[0:1]
	s_waitcnt lgkmcnt(0)
	s_barrier
	ds_read_b32 v0, v242
	s_mov_b64 s[0:1], -1
	s_waitcnt lgkmcnt(0)
	v_readfirstlane_b32 s2, v0
	s_cmpk_gt_i32 s2, 0x32f
	s_cbranch_scc1 .LBB0_784
	s_mul_hi_i32 s0, s2, 0x78787879
	s_lshr_b32 s1, s0, 31
	s_ashr_i32 s0, s0, 6
	s_add_i32 s1, s0, s1
	s_mul_i32 s0, s1, 0x88
	s_sub_i32 s2, s2, s0
	s_ashr_i32 s14, s2, 3
	s_lshl_b32 s2, s2, 3
	s_lshl_b32 s1, s1, 6
	s_and_b32 s2, s2, 56
	v_mov_b32_e32 v0, v234
	s_or_b32 s1, s2, s1
	s_lshl_b32 s12, s14, 8
	v_add_u32_e32 v247, s33, v0
	s_or_b32 s64, s1, s97
	s_ashr_i32 s13, s12, 31
	v_readfirstlane_b32 s15, v247
	s_ashr_i32 s1, s15, 6
	s_ashr_i32 s72, s15, 7
	s_lshl_b32 s92, s64, 7
	s_lshl_b64 s[2:3], s[12:13], 11
	s_add_u32 s4, s62, s2
	s_addc_u32 s5, s63, s3
	s_ashr_i32 s93, s92, 31
	s_lshl_b64 s[2:3], s[92:93], 11
	s_add_u32 s8, s48, s2
	v_lshlrev_b32_e32 v2, 4, v247
	s_addc_u32 s2, s49, s3
	v_lshlrev_b32_e32 v1, 9, v247
	v_bitop3_b32 v2, v2, 48, v247 bitop3:0x48
	s_and_b32 s3, s1, 1
	s_lshl_b32 s1, s1, 10
	v_and_or_b32 v181, v1, s80, v2
	s_and_b32 s5, s5, 0xffff
	s_mov_b32 m0, s1
	v_add_u32_e32 v182, 0x20000, v181
	s_waitcnt vmcnt(0)
	s_barrier
	buffer_load_dwordx4 v181, s[4:7], 0 offen lds
	s_add_i32 m0, s1, 0x1000
	v_add_u32_e32 v183, 0x40000, v181
	buffer_load_dwordx4 v182, s[4:7], 0 offen lds
	s_add_i32 m0, s1, 0x2000
	v_add_u32_e32 v184, 0x60000, v181
	v_add_u32_e32 v248, 0x100, v247
	buffer_load_dwordx4 v183, s[4:7], 0 offen lds
	s_add_i32 m0, s1, 0x3000
	s_and_b32 s9, s2, 0xffff
	s_mov_b32 s10, s6
	s_mov_b32 s11, s7
	buffer_load_dwordx4 v184, s[4:7], 0 offen lds
	s_add_i32 m0, s1, 0x4000
	v_lshlrev_b32_e32 v1, 9, v248
	buffer_load_dwordx4 v181, s[8:11], 0 offen lds
	s_add_i32 m0, s1, 0x5000
	v_and_or_b32 v185, v1, s80, v2
	buffer_load_dwordx4 v185, s[8:11], 0 offen lds
	s_add_i32 m0, s1, 0x6000
	v_lshrrev_b32_e32 v0, 5, v247
	buffer_load_dwordx4 v181, s[4:7], 64 offen lds
	s_add_i32 m0, s1, 0x7000
	v_and_b32_e32 v202, 31, v247
	buffer_load_dwordx4 v182, s[4:7], 64 offen lds
	s_add_i32 m0, s1, 0x8000
	v_bfe_u32 v3, v247, 2, 2
	buffer_load_dwordx4 v183, s[4:7], 64 offen lds
	s_add_i32 m0, s1, 0x9000
	v_lshlrev_b32_e32 v1, 5, v202
	buffer_load_dwordx4 v184, s[4:7], 64 offen lds
	s_add_i32 m0, s1, 0xa000
	v_bitop3_b32 v0, v0, v3, 1 bitop3:0x6c
	buffer_load_dwordx4 v181, s[8:11], 64 offen lds
	s_add_i32 m0, s1, 0xb000
	s_and_b32 s2, s15, 0x7ffff80
	buffer_load_dwordx4 v185, s[8:11], 64 offen lds
	s_add_i32 m0, s1, 0xc000
	v_lshl_or_b32 v2, s72, 12, v1
	buffer_load_dwordx4 v181, s[4:7], s81 offen lds
	s_add_i32 m0, s1, 0xd000
	v_lshlrev_b32_e32 v0, 3, v0
	buffer_load_dwordx4 v182, s[4:7], s81 offen lds
	s_add_i32 m0, s1, 0xe000
	v_or_b32_e32 v4, s2, v202
	buffer_load_dwordx4 v183, s[4:7], s81 offen lds
	s_add_i32 m0, s1, 0xf000
	v_or_b32_e32 v189, v0, v2
	buffer_load_dwordx4 v184, s[4:7], s81 offen lds
	s_add_i32 m0, s1, 0x10000
	v_lshlrev_b32_e32 v4, 5, v4
	buffer_load_dwordx4 v181, s[8:11], s81 offen lds
	s_add_i32 m0, s1, 0x11000
	s_lshl_b32 s65, s3, 6
	buffer_load_dwordx4 v185, s[8:11], s81 offen lds
	v_lshlrev_b32_e32 v177, 1, v189
	v_or_b32_e32 v190, v4, v0
	v_lshl_or_b32 v1, s3, 11, v1
	v_or_b32_e32 v200, s65, v202
	v_readlane_b32 s98, v249, 10
	v_readlane_b32 s99, v249, 11
	v_or_b32_e32 v206, s92, v200
	v_ashrrev_i32_e32 v207, 31, v206
	v_lshl_add_u64 v[206:207], v[206:207], 2, s[98:99]
	global_load_dword v204, v[206:207], off
	global_load_dword v205, v[206:207], off offset:128
	s_waitcnt vmcnt(12)
	s_waitcnt vmcnt(0)
	s_barrier
; #define MFMA32(a, b, c) __builtin_amdgcn_mfma_f32_32x32x16_bf16((a), (b), (c), 0, 0, 0)
; template <bool IN_PROJ>
; DI void gemm_tile(const Params& p, int layer, int nt, int tt, char* smem) {
;     ...
;   f32x16 acc[4][2];
; #pragma unroll
;   for (int a = 0; a < 4; ++a)
; #pragma unroll
;     for (int b = 0; b < 2; ++b)
; #pragma unroll
;       for (int i = 0; i < 16; ++i) acc[a][b][i] = 0.f;
;     ...
;   auto load_frags = [&](int kt, int ks, bf16x8 (&fa)[4], bf16x8 (&fb)[2]) {
;     const u16* sA = (const u16*)(smem + (kt % 3) * G_STAGE);
;     const u16* sB = sA + 8192;
; #pragma unroll
;     for (int fi = 0; fi < 4; ++fi) fa[fi] = *(const bf16x8*)(sA + gswz(wf * 128 + fi * 32 + r, ks * 2 + h));
; #pragma unroll
;     for (int ti = 0; ti < 2; ++ti) fb[ti] = *(const bf16x8*)(sB + gswz(wt * 64 + ti * 32 + r, ks * 2 + h));
;   };
;   auto mma = [&](const bf16x8 (&fa)[4], const bf16x8 (&fb)[2]) {
; #pragma unroll
;     for (int fi = 0; fi < 4; ++fi)
; #pragma unroll
;       for (int ti = 0; ti < 2; ++ti) acc[fi][ti] = MFMA32(fa[fi], fb[ti], acc[fi][ti]);
;   };
;   bf16x8 fa0[4], fb0[2], fa1[4], fb1[2];
;   asm volatile("s_waitcnt vmcnt(12)" ::: "memory");
;   __syncthreads();
;   load_frags(0, 0, fa0, fb0);
	v_lshlrev_b32_e32 v176, 1, v190
	ds_read_b128 v[132:135], v177
	ds_read_b128 v[104:107], v176 offset:2048
	ds_read_b128 v[100:103], v176 offset:4096
	ds_read_b128 v[96:99], v176 offset:6144
	v_or_b32_e32 v191, v1, v0
	v_lshlrev_b32_e32 v5, 5, v200
	v_lshlrev_b32_e32 v178, 1, v191
	v_or_b32_e32 v192, v5, v0
	v_lshlrev_b32_e32 v179, 1, v192
	ds_read_b128 v[128:131], v178 offset:16384
	ds_read_b128 v[108:111], v179 offset:18432
	v_bfe_u32 v201, v247, 5, 1
	v_bitop3_b32 v0, v201, v3, 2 bitop3:0x36
	v_lshlrev_b32_e32 v0, 3, v0
	v_mov_b32_e32 v64, 0
	s_mov_b32 s0, 3
	v_or_b32_e32 v188, v0, v2
	v_or_b32_e32 v187, v0, v1
	v_or_b32_e32 v186, v0, v4
	v_or_b32_e32 v180, v5, v0
	s_movk_i32 s2, 0xc0
	v_mov_b32_e32 v65, v64
	v_mov_b32_e32 v66, v64
	v_mov_b32_e32 v67, v64
	v_mov_b32_e32 v68, v64
	v_mov_b32_e32 v69, v64
	v_mov_b32_e32 v70, v64
	v_mov_b32_e32 v71, v64
	v_mov_b32_e32 v72, v64
	v_mov_b32_e32 v73, v64
	v_mov_b32_e32 v74, v64
	v_mov_b32_e32 v75, v64
	v_mov_b32_e32 v76, v64
	v_mov_b32_e32 v77, v64
	v_mov_b32_e32 v78, v64
	v_mov_b32_e32 v79, v64
	v_mov_b32_e32 v0, v64
	v_mov_b32_e32 v1, v64
	v_mov_b32_e32 v2, v64
	v_mov_b32_e32 v3, v64
	v_mov_b32_e32 v4, v64
	v_mov_b32_e32 v5, v64
	v_mov_b32_e32 v6, v64
	v_mov_b32_e32 v7, v64
	v_mov_b32_e32 v8, v64
	v_mov_b32_e32 v9, v64
	v_mov_b32_e32 v10, v64
	v_mov_b32_e32 v11, v64
	v_mov_b32_e32 v12, v64
	v_mov_b32_e32 v13, v64
	v_mov_b32_e32 v14, v64
	v_mov_b32_e32 v15, v64
	v_mov_b32_e32 v80, v64
	v_mov_b32_e32 v81, v64
	v_mov_b32_e32 v82, v64
	v_mov_b32_e32 v83, v64
	v_mov_b32_e32 v84, v64
	v_mov_b32_e32 v85, v64
	v_mov_b32_e32 v86, v64
	v_mov_b32_e32 v87, v64
	v_mov_b32_e32 v88, v64
	v_mov_b32_e32 v89, v64
	v_mov_b32_e32 v90, v64
	v_mov_b32_e32 v91, v64
	v_mov_b32_e32 v92, v64
	v_mov_b32_e32 v93, v64
	v_mov_b32_e32 v94, v64
	v_mov_b32_e32 v95, v64
	v_mov_b32_e32 v16, v64
	v_mov_b32_e32 v17, v64
	v_mov_b32_e32 v18, v64
	v_mov_b32_e32 v19, v64
	v_mov_b32_e32 v20, v64
	v_mov_b32_e32 v21, v64
	v_mov_b32_e32 v22, v64
	v_mov_b32_e32 v23, v64
	v_mov_b32_e32 v24, v64
	v_mov_b32_e32 v25, v64
	v_mov_b32_e32 v26, v64
	v_mov_b32_e32 v27, v64
	v_mov_b32_e32 v28, v64
	v_mov_b32_e32 v29, v64
	v_mov_b32_e32 v30, v64
	v_mov_b32_e32 v31, v64
	v_mov_b32_e32 v112, v64
	v_mov_b32_e32 v113, v64
	v_mov_b32_e32 v114, v64
	v_mov_b32_e32 v115, v64
	v_mov_b32_e32 v116, v64
	v_mov_b32_e32 v117, v64
	v_mov_b32_e32 v118, v64
	v_mov_b32_e32 v119, v64
	v_mov_b32_e32 v120, v64
	v_mov_b32_e32 v121, v64
	v_mov_b32_e32 v122, v64
	v_mov_b32_e32 v123, v64
	v_mov_b32_e32 v124, v64
	v_mov_b32_e32 v125, v64
	v_mov_b32_e32 v126, v64
	v_mov_b32_e32 v127, v64
	v_mov_b32_e32 v32, v64
	v_mov_b32_e32 v33, v64
	v_mov_b32_e32 v34, v64
	v_mov_b32_e32 v35, v64
	v_mov_b32_e32 v36, v64
	v_mov_b32_e32 v37, v64
	v_mov_b32_e32 v38, v64
	v_mov_b32_e32 v39, v64
	v_mov_b32_e32 v40, v64
	v_mov_b32_e32 v41, v64
	v_mov_b32_e32 v42, v64
	v_mov_b32_e32 v43, v64
	v_mov_b32_e32 v44, v64
	v_mov_b32_e32 v45, v64
	v_mov_b32_e32 v46, v64
	v_mov_b32_e32 v47, v64
	v_mov_b32_e32 v144, v64
	v_mov_b32_e32 v145, v64
	v_mov_b32_e32 v146, v64
	v_mov_b32_e32 v147, v64
	v_mov_b32_e32 v148, v64
	v_mov_b32_e32 v149, v64
	v_mov_b32_e32 v150, v64
	v_mov_b32_e32 v151, v64
	v_mov_b32_e32 v152, v64
	v_mov_b32_e32 v153, v64
	v_mov_b32_e32 v154, v64
	v_mov_b32_e32 v155, v64
	v_mov_b32_e32 v156, v64
	v_mov_b32_e32 v157, v64
	v_mov_b32_e32 v158, v64
	v_mov_b32_e32 v159, v64
	v_mov_b32_e32 v48, v64
	v_mov_b32_e32 v49, v64
	v_mov_b32_e32 v50, v64
	v_mov_b32_e32 v51, v64
	v_mov_b32_e32 v52, v64
	v_mov_b32_e32 v53, v64
	v_mov_b32_e32 v54, v64
	v_mov_b32_e32 v55, v64
	v_mov_b32_e32 v56, v64
	v_mov_b32_e32 v57, v64
	v_mov_b32_e32 v58, v64
	v_mov_b32_e32 v59, v64
	v_mov_b32_e32 v60, v64
	v_mov_b32_e32 v61, v64
	v_mov_b32_e32 v62, v64
	v_mov_b32_e32 v63, v64

; DI float sigm(float x) { return __builtin_amdgcn_rcpf(1.f + __builtin_amdgcn_exp2f(-LOG2E * x)); }
; template <bool IN_PROJ>
; DI void gemm_tile(const Params& p, int layer, int nt, int tt, char* smem) {
;     ...
;   const float* rstd = (const float*)(p.ws + WS_RSTD);
;   u32* misc = (u32*)(p.ws + WS_MISC);
;   const float* miscf = (const float*)misc;
;   u16* sC = (u16*)(smem + wf * 34816);
; #pragma unroll
;   for (int ti = 0; ti < 2; ++ti) {
;     const int t = t0 + wt * 64 + ti * 32 + r;
;     const float rs = rstd[t];
; #pragma unroll
;     for (int fi = 0; fi < 4; ++fi)
; #pragma unroll
;       for (int i = 0; i < 16; ++i) acc[fi][ti][i] *= rs;
;     if (d.kind == K_SILU) {
; #pragma unroll
;       for (int fi = 0; fi < 4; ++fi)
; #pragma unroll
;         for (int i = 0; i < 16; ++i) { float x = acc[fi][ti][i]; acc[fi][ti][i] = x * sigm(x); }
;     } else if (d.kind == K_G) {
; #pragma unroll
;       for (int fi = 0; fi < 4; ++fi)
; #pragma unroll
;         for (int g = 0; g < 4; ++g) {
;           float4 lb4 = make_float4(0.f, 0.f, 0.f, 0.f);
;           if (layer != 0) lb4 = *(const float4*)(miscf + 128 + d.aux * 512 + d.col + fi * 32 + 8 * g + 4 * h);
.LBB0_834:
	s_xor_b64 s[8:9], s[2:3], -1
	s_xor_b64 s[4:5], s[4:5], -1
	s_lshl_b64 s[2:3], s[10:11], 2
	s_add_u32 s2, s66, s2
	s_addc_u32 s3, s67, s3
	s_ashr_i32 s1, s0, 31
	s_lshl_b64 s[0:1], s[0:1], 2
	s_add_u32 s0, s2, s0
	s_addc_u32 s1, s3, s1
	v_lshlrev_b32_e32 v192, 4, v201
	v_or_b32_e32 v96, s92, v200
	v_lshl_add_u64 v[194:195], s[0:1], 0, v[192:193]
	v_readlane_b32 s0, v249, 10
	v_ashrrev_i32_e32 v97, 31, v96
	v_readlane_b32 s1, v249, 11
	s_mov_b64 s[60:61], -1
	s_mov_b64 s[90:91], 0
	v_lshl_add_u64 v[196:197], v[96:97], 2, s[0:1]
	v_mov_b32_e32 v160, v204
	s_cmp_lt_i32 s13, 2
	s_mov_b64 s[10:11], 0
	s_mov_b64 s[0:1], 0
	s_mov_b64 s[2:3], 0
	s_waitcnt vmcnt(0)
	v_pk_mul_f32 v[128:129], v[64:65], v[160:161] op_sel_hi:[1,0]
	v_pk_mul_f32 v[130:131], v[66:67], v[160:161] op_sel_hi:[1,0]
	v_pk_mul_f32 v[132:133], v[68:69], v[160:161] op_sel_hi:[1,0]
	v_pk_mul_f32 v[134:135], v[70:71], v[160:161] op_sel_hi:[1,0]
	v_pk_mul_f32 v[136:137], v[72:73], v[160:161] op_sel_hi:[1,0]
	v_pk_mul_f32 v[138:139], v[74:75], v[160:161] op_sel_hi:[1,0]
	v_pk_mul_f32 v[140:141], v[76:77], v[160:161] op_sel_hi:[1,0]
	v_pk_mul_f32 v[142:143], v[78:79], v[160:161] op_sel_hi:[1,0]
	v_pk_mul_f32 v[96:97], v[80:81], v[160:161] op_sel_hi:[1,0]
	v_pk_mul_f32 v[98:99], v[82:83], v[160:161] op_sel_hi:[1,0]
	v_pk_mul_f32 v[100:101], v[84:85], v[160:161] op_sel_hi:[1,0]
	v_pk_mul_f32 v[102:103], v[86:87], v[160:161] op_sel_hi:[1,0]
	v_pk_mul_f32 v[104:105], v[88:89], v[160:161] op_sel_hi:[1,0]
	v_pk_mul_f32 v[106:107], v[90:91], v[160:161] op_sel_hi:[1,0]
	v_pk_mul_f32 v[108:109], v[92:93], v[160:161] op_sel_hi:[1,0]
	v_pk_mul_f32 v[110:111], v[94:95], v[160:161] op_sel_hi:[1,0]
	v_pk_mul_f32 v[80:81], v[112:113], v[160:161] op_sel_hi:[1,0]
	v_pk_mul_f32 v[82:83], v[114:115], v[160:161] op_sel_hi:[1,0]
	v_pk_mul_f32 v[84:85], v[116:117], v[160:161] op_sel_hi:[1,0]
	v_pk_mul_f32 v[86:87], v[118:119], v[160:161] op_sel_hi:[1,0]
	v_pk_mul_f32 v[88:89], v[120:121], v[160:161] op_sel_hi:[1,0]
	v_pk_mul_f32 v[90:91], v[122:123], v[160:161] op_sel_hi:[1,0]
	v_pk_mul_f32 v[92:93], v[124:125], v[160:161] op_sel_hi:[1,0]
	v_pk_mul_f32 v[94:95], v[126:127], v[160:161] op_sel_hi:[1,0]
	v_pk_mul_f32 v[64:65], v[144:145], v[160:161] op_sel_hi:[1,0]
	v_pk_mul_f32 v[66:67], v[146:147], v[160:161] op_sel_hi:[1,0]
	v_pk_mul_f32 v[68:69], v[148:149], v[160:161] op_sel_hi:[1,0]
	v_pk_mul_f32 v[70:71], v[150:151], v[160:161] op_sel_hi:[1,0]
	v_pk_mul_f32 v[72:73], v[152:153], v[160:161] op_sel_hi:[1,0]
	v_pk_mul_f32 v[74:75], v[154:155], v[160:161] op_sel_hi:[1,0]
	v_pk_mul_f32 v[76:77], v[156:157], v[160:161] op_sel_hi:[1,0]
	v_pk_mul_f32 v[78:79], v[158:159], v[160:161] op_sel_hi:[1,0]
	s_cbranch_scc1 .LBB0_846
	s_cmp_gt_i32 s13, 4
	s_cbranch_scc0 .LBB0_838
	s_mov_b64 s[2:3], -1
	s_mov_b64 s[60:61], 0
	s_cmp_eq_u32 s13, 5
	s_cbranch_scc0 .LBB0_838
	s_mov_b64 s[2:3], 0
	s_mov_b64 s[10:11], -1

; template <bool IN_PROJ>
; DI void gemm_tile(const Params& p, int layer, int nt, int tt, char* smem) {
;     ...
;   for (int ti = 0; ti < 2; ++ti) {
;     const int t = t0 + wt * 64 + ti * 32 + r;
;     const float rs = rstd[t];
; #pragma unroll
;     for (int fi = 0; fi < 4; ++fi)
; #pragma unroll
;       for (int i = 0; i < 16; ++i) acc[fi][ti][i] *= rs;
;     if (d.kind == K_SILU) {
.LBB0_918:
	v_mov_b32_e32 v96, v205
	s_mov_b64 s[60:61], -1
	s_mov_b64 s[90:91], 0
	s_cmp_lt_i32 s13, 2
	s_mov_b64 s[10:11], 0
	s_mov_b64 s[0:1], 0
	s_mov_b64 s[2:3], 0
	s_waitcnt vmcnt(0)
	v_pk_mul_f32 v[80:81], v[0:1], v[96:97] op_sel_hi:[1,0]
	v_pk_mul_f32 v[82:83], v[2:3], v[96:97] op_sel_hi:[1,0]
	v_pk_mul_f32 v[84:85], v[4:5], v[96:97] op_sel_hi:[1,0]
	v_pk_mul_f32 v[86:87], v[6:7], v[96:97] op_sel_hi:[1,0]
	v_pk_mul_f32 v[88:89], v[8:9], v[96:97] op_sel_hi:[1,0]
	v_pk_mul_f32 v[90:91], v[10:11], v[96:97] op_sel_hi:[1,0]
	v_pk_mul_f32 v[92:93], v[12:13], v[96:97] op_sel_hi:[1,0]
	v_pk_mul_f32 v[94:95], v[14:15], v[96:97] op_sel_hi:[1,0]
	v_pk_mul_f32 v[64:65], v[16:17], v[96:97] op_sel_hi:[1,0]
	v_pk_mul_f32 v[66:67], v[18:19], v[96:97] op_sel_hi:[1,0]
	v_pk_mul_f32 v[68:69], v[20:21], v[96:97] op_sel_hi:[1,0]
	v_pk_mul_f32 v[70:71], v[22:23], v[96:97] op_sel_hi:[1,0]
	v_pk_mul_f32 v[72:73], v[24:25], v[96:97] op_sel_hi:[1,0]
	v_pk_mul_f32 v[74:75], v[26:27], v[96:97] op_sel_hi:[1,0]
	v_pk_mul_f32 v[76:77], v[28:29], v[96:97] op_sel_hi:[1,0]
	v_pk_mul_f32 v[78:79], v[30:31], v[96:97] op_sel_hi:[1,0]
	v_pk_mul_f32 v[16:17], v[32:33], v[96:97] op_sel_hi:[1,0]
	v_pk_mul_f32 v[18:19], v[34:35], v[96:97] op_sel_hi:[1,0]
	v_pk_mul_f32 v[20:21], v[36:37], v[96:97] op_sel_hi:[1,0]
	v_pk_mul_f32 v[22:23], v[38:39], v[96:97] op_sel_hi:[1,0]
	v_pk_mul_f32 v[24:25], v[40:41], v[96:97] op_sel_hi:[1,0]
	v_pk_mul_f32 v[26:27], v[42:43], v[96:97] op_sel_hi:[1,0]
	v_pk_mul_f32 v[28:29], v[44:45], v[96:97] op_sel_hi:[1,0]
	v_pk_mul_f32 v[30:31], v[46:47], v[96:97] op_sel_hi:[1,0]
	v_pk_mul_f32 v[0:1], v[48:49], v[96:97] op_sel_hi:[1,0]
	v_pk_mul_f32 v[2:3], v[50:51], v[96:97] op_sel_hi:[1,0]
	v_pk_mul_f32 v[4:5], v[52:53], v[96:97] op_sel_hi:[1,0]
	v_pk_mul_f32 v[6:7], v[54:55], v[96:97] op_sel_hi:[1,0]
	v_pk_mul_f32 v[8:9], v[56:57], v[96:97] op_sel_hi:[1,0]
	v_pk_mul_f32 v[10:11], v[58:59], v[96:97] op_sel_hi:[1,0]
	v_pk_mul_f32 v[12:13], v[60:61], v[96:97] op_sel_hi:[1,0]
	v_pk_mul_f32 v[14:15], v[62:63], v[96:97] op_sel_hi:[1,0]
	s_cbranch_scc1 .LBB0_934
	s_cmp_gt_i32 s13, 4
	s_cbranch_scc0 .LBB0_922
	s_mov_b64 s[2:3], -1
	s_mov_b64 s[60:61], 0
	s_cmp_eq_u32 s13, 5
	s_cbranch_scc0 .LBB0_922
	s_mov_b64 s[2:3], 0
	s_mov_b64 s[10:11], -1

; __global__ void __launch_bounds__(256, 2) hymba_mega(Params p0) {
;   __shared__ __attribute__((aligned(16))) char smem[SMEM_BYTES];
	.amdhsa_kernel _Z10hymba_mega6Params
		.amdhsa_group_segment_fixed_size 79888
		.amdhsa_private_segment_fixed_size 0
		.amdhsa_kernarg_size 376
		.amdhsa_user_sgpr_count 2
		.amdhsa_user_sgpr_dispatch_ptr 0
		.amdhsa_user_sgpr_queue_ptr 0
		.amdhsa_user_sgpr_kernarg_segment_ptr 1
		.amdhsa_user_sgpr_dispatch_id 0
		.amdhsa_user_sgpr_kernarg_preload_length 0
		.amdhsa_user_sgpr_kernarg_preload_offset 0
		.amdhsa_user_sgpr_private_segment_size 0
		.amdhsa_uses_dynamic_stack 0
		.amdhsa_enable_private_segment 0
		.amdhsa_system_sgpr_workgroup_id_x 1
		.amdhsa_system_sgpr_workgroup_id_y 0
		.amdhsa_system_sgpr_workgroup_id_z 0
		.amdhsa_system_sgpr_workgroup_info 0
		.amdhsa_system_vgpr_workitem_id 2
		.amdhsa_next_free_vgpr 254
		.amdhsa_next_free_sgpr 102
		.amdhsa_accum_offset 256
		.amdhsa_reserve_vcc 1
		.amdhsa_float_round_mode_32 0
		.amdhsa_float_round_mode_16_64 0
		.amdhsa_float_denorm_mode_32 3
		.amdhsa_float_denorm_mode_16_64 3
		.amdhsa_dx10_clamp 1
		.amdhsa_ieee_mode 1
		.amdhsa_fp16_overflow 0
		.amdhsa_tg_split 0
		.amdhsa_exception_fp_ieee_invalid_op 0
		.amdhsa_exception_fp_denorm_src 0
		.amdhsa_exception_fp_ieee_div_zero 0
		.amdhsa_exception_fp_ieee_overflow 0
		.amdhsa_exception_fp_ieee_underflow 0
		.amdhsa_exception_fp_ieee_inexact 0
		.amdhsa_exception_int_div_zero 0
	.end_amdhsa_kernel

; __global__ void __launch_bounds__(256, 2) hymba_mega(Params p0) {
;   __shared__ __attribute__((aligned(16))) char smem[SMEM_BYTES];
amdhsa.kernels:
  - .agpr_count:     0
    .args:
      - .offset:         0
        .size:           120
        .value_kind:     by_value
      - .offset:         120
        .size:           4
        .value_kind:     hidden_block_count_x
      - .offset:         124
        .size:           4
        .value_kind:     hidden_block_count_y
      - .offset:         128
        .size:           4
        .value_kind:     hidden_block_count_z
      - .offset:         132
        .size:           2
        .value_kind:     hidden_group_size_x
      - .offset:         134
        .size:           2
        .value_kind:     hidden_group_size_y
      - .offset:         136
        .size:           2
        .value_kind:     hidden_group_size_z
      - .offset:         138
        .size:           2
        .value_kind:     hidden_remainder_x
      - .offset:         140
        .size:           2
        .value_kind:     hidden_remainder_y
      - .offset:         142
        .size:           2
        .value_kind:     hidden_remainder_z
      - .offset:         160
        .size:           8
        .value_kind:     hidden_global_offset_x
      - .offset:         168
        .size:           8
        .value_kind:     hidden_global_offset_y
      - .offset:         176
        .size:           8
        .value_kind:     hidden_global_offset_z
      - .offset:         184
        .size:           2
        .value_kind:     hidden_grid_dims
      - .offset:         208
        .size:           8
        .value_kind:     hidden_multigrid_sync_arg
    .group_segment_fixed_size: 79888
    .kernarg_segment_align: 8
    .kernarg_segment_size: 376
    .language:       OpenCL C
    .language_version:
      - 2
      - 0
    .max_flat_workgroup_size: 256
    .name:           _Z10hymba_mega6Params
    .private_segment_fixed_size: 0
    .sgpr_count:     108
    .sgpr_spill_count: 53
    .symbol:         _Z10hymba_mega6Params.kd
    .uniform_work_group_size: 1
    .uses_dynamic_stack: false
    .vgpr_count:     254
    .vgpr_spill_count: 0
    .wavefront_size: 64
